# strategy 1 on the GEMM mainloops: the redundant lgkmcnt(0) wait after each MMA-segment barrier (already waited before the barrier) removed, 16 sites
# baseline (speedup 1.0000x reference)
.LBB0_176:
	s_add_u32 s2, s14, 0xfffc0080
	s_addc_u32 s3, s15, -1
	s_add_i32 s47, 0, 0x10000
	s_cmp_eq_u32 s46, 12
	s_cselect_b32 s25, s7, s3
	s_cselect_b32 s24, s11, s2
	v_add_u32_e32 v0, s47, v155
	s_cselect_b32 s3, s13, s33
	s_cselect_b32 s2, s29, s31
	s_add_i32 s54, 0, 0x14000
	ds_read_b128 v[50:53], v0
	ds_read_b128 v[54:57], v0 offset:1024
	ds_read_b128 v[58:61], v0 offset:2048
	ds_read_b128 v[62:65], v0 offset:3072
	v_add_u32_e32 v0, s54, v155
	ds_read_b128 v[176:179], v0
	ds_read_b128 v[188:191], v0 offset:1024
	ds_read_b128 v[192:195], v0 offset:2048
	ds_read_b128 v[196:199], v0 offset:3072
	v_lshl_add_u64 v[180:181], s[14:15], 0, v[170:171]
	s_add_i32 m0, s90, 0xc000
	ds_read_b128 v[200:203], v186
	ds_read_b128 v[204:207], v186 offset:1024
	ds_read_b128 v[226:229], v186 offset:2048
	ds_read_b128 v[230:233], v186 offset:3072
	ds_read_b128 v[234:237], v186 offset:4096
	ds_read_b128 v[238:241], v186 offset:5120
	ds_read_b128 v[242:245], v186 offset:6144
	ds_read_b128 v[246:249], v186 offset:7168
	global_load_lds_dwordx4 v[180:181], off
	v_lshl_add_u64 v[180:181], s[14:15], 0, v[172:173]
	s_add_i32 m0, s90, 0xe000
	s_nop 0
	global_load_lds_dwordx4 v[180:181], off
	s_waitcnt vmcnt(8)
	s_waitcnt lgkmcnt(0)
	s_barrier
	s_setprio 1
	v_mfma_f32_16x16x32_bf16 v[142:145], v[50:53], v[200:203], v[142:145]
	v_mfma_f32_16x16x32_bf16 v[138:141], v[58:61], v[200:203], v[138:141]
	v_mfma_f32_16x16x32_bf16 v[126:129], v[50:53], v[226:229], v[126:129]
	v_mfma_f32_16x16x32_bf16 v[122:125], v[58:61], v[226:229], v[122:125]
	v_mfma_f32_16x16x32_bf16 v[110:113], v[50:53], v[234:237], v[110:113]
	v_mfma_f32_16x16x32_bf16 v[106:109], v[58:61], v[234:237], v[106:109]
	v_mfma_f32_16x16x32_bf16 v[94:97], v[50:53], v[242:245], v[94:97]
	v_mfma_f32_16x16x32_bf16 v[90:93], v[58:61], v[242:245], v[90:93]
	v_mfma_f32_16x16x32_bf16 v[142:145], v[54:57], v[204:207], v[142:145]
	v_mfma_f32_16x16x32_bf16 v[138:141], v[62:65], v[204:207], v[138:141]
	v_mfma_f32_16x16x32_bf16 v[126:129], v[54:57], v[230:233], v[126:129]
	v_mfma_f32_16x16x32_bf16 v[122:125], v[62:65], v[230:233], v[122:125]
	v_mfma_f32_16x16x32_bf16 v[110:113], v[54:57], v[238:241], v[110:113]
	v_mfma_f32_16x16x32_bf16 v[106:109], v[62:65], v[238:241], v[106:109]
	v_mfma_f32_16x16x32_bf16 v[94:97], v[54:57], v[246:249], v[94:97]
	v_mfma_f32_16x16x32_bf16 v[90:93], v[62:65], v[246:249], v[90:93]
	s_setprio 0
	s_setprio 1
	v_mfma_f32_16x16x32_bf16 v[134:137], v[176:179], v[200:203], v[134:137]
	v_mfma_f32_16x16x32_bf16 v[130:133], v[192:195], v[200:203], v[130:133]
	v_mfma_f32_16x16x32_bf16 v[118:121], v[176:179], v[226:229], v[118:121]
	v_mfma_f32_16x16x32_bf16 v[114:117], v[192:195], v[226:229], v[114:117]
	v_mfma_f32_16x16x32_bf16 v[102:105], v[176:179], v[234:237], v[102:105]
	v_mfma_f32_16x16x32_bf16 v[98:101], v[192:195], v[234:237], v[98:101]
	v_mfma_f32_16x16x32_bf16 v[86:89], v[176:179], v[242:245], v[86:89]
	v_mfma_f32_16x16x32_bf16 v[82:85], v[192:195], v[242:245], v[82:85]
	v_mfma_f32_16x16x32_bf16 v[134:137], v[188:191], v[204:207], v[134:137]
	v_mfma_f32_16x16x32_bf16 v[130:133], v[196:199], v[204:207], v[130:133]
	v_mfma_f32_16x16x32_bf16 v[118:121], v[188:191], v[230:233], v[118:121]
	v_mfma_f32_16x16x32_bf16 v[114:117], v[196:199], v[230:233], v[114:117]
	v_mfma_f32_16x16x32_bf16 v[102:105], v[188:191], v[238:241], v[102:105]
	v_mfma_f32_16x16x32_bf16 v[98:101], v[196:199], v[238:241], v[98:101]
	v_mfma_f32_16x16x32_bf16 v[86:89], v[188:191], v[246:249], v[86:89]
	v_mfma_f32_16x16x32_bf16 v[82:85], v[196:199], v[246:249], v[82:85]
	s_setprio 0
	s_barrier
	s_add_i32 s47, s47, s42
	v_lshl_add_u64 v[180:181], s[2:3], 0, v[146:147]
	s_mov_b32 m0, s47
	ds_read_b128 v[200:203], v186 offset:16384
	ds_read_b128 v[204:207], v186 offset:17408
	ds_read_b128 v[226:229], v186 offset:18432
	ds_read_b128 v[230:233], v186 offset:19456
	ds_read_b128 v[234:237], v186 offset:20480
	ds_read_b128 v[238:241], v186 offset:21504
	ds_read_b128 v[242:245], v186 offset:22528
	ds_read_b128 v[246:249], v186 offset:23552
	global_load_lds_dwordx4 v[180:181], off
	s_add_i32 m0, s47, 0x2000
	s_add_u32 s58, s2, 0x40000
	v_lshl_add_u64 v[222:223], s[2:3], 0, v[148:149]
	s_addc_u32 s59, s3, 0
	s_add_i32 s47, s54, s42
	global_load_lds_dwordx4 v[222:223], off
	v_lshl_add_u64 v[224:225], s[58:59], 0, v[146:147]
	s_mov_b32 m0, s47
	v_lshl_add_u64 v[250:251], s[24:25], 0, v[148:149]
	global_load_lds_dwordx4 v[224:225], off
	v_lshl_add_u64 v[224:225], s[58:59], 0, v[148:149]
	s_add_i32 m0, s47, 0x2000
	s_nop 0
	global_load_lds_dwordx4 v[224:225], off
	v_lshl_add_u64 v[224:225], s[24:25], 0, v[146:147]
	s_mov_b32 m0, s90
	s_nop 0
	global_load_lds_dwordx4 v[224:225], off
	s_mov_b32 m0, s91
	s_nop 0
	global_load_lds_dwordx4 v[250:251], off
	s_waitcnt vmcnt(8)
	s_waitcnt lgkmcnt(0)
	s_barrier
	s_setprio 1
	v_mfma_f32_16x16x32_bf16 v[78:81], v[50:53], v[200:203], v[78:81]
	v_mfma_f32_16x16x32_bf16 v[74:77], v[58:61], v[200:203], v[74:77]
	v_mfma_f32_16x16x32_bf16 v[46:49], v[50:53], v[226:229], v[46:49]
	v_mfma_f32_16x16x32_bf16 v[42:45], v[58:61], v[226:229], v[42:45]
	v_mfma_f32_16x16x32_bf16 v[30:33], v[50:53], v[234:237], v[30:33]
	v_mfma_f32_16x16x32_bf16 v[26:29], v[58:61], v[234:237], v[26:29]
	v_mfma_f32_16x16x32_bf16 v[14:17], v[50:53], v[242:245], v[14:17]
	v_mfma_f32_16x16x32_bf16 v[10:13], v[58:61], v[242:245], v[10:13]
	v_mfma_f32_16x16x32_bf16 v[78:81], v[54:57], v[204:207], v[78:81]
	v_mfma_f32_16x16x32_bf16 v[74:77], v[62:65], v[204:207], v[74:77]
	v_mfma_f32_16x16x32_bf16 v[46:49], v[54:57], v[230:233], v[46:49]
	v_mfma_f32_16x16x32_bf16 v[42:45], v[62:65], v[230:233], v[42:45]
	v_mfma_f32_16x16x32_bf16 v[30:33], v[54:57], v[238:241], v[30:33]
	v_mfma_f32_16x16x32_bf16 v[26:29], v[62:65], v[238:241], v[26:29]
	v_mfma_f32_16x16x32_bf16 v[14:17], v[54:57], v[246:249], v[14:17]
	v_mfma_f32_16x16x32_bf16 v[10:13], v[62:65], v[246:249], v[10:13]
	s_setprio 0
	s_setprio 1
	v_mfma_f32_16x16x32_bf16 v[38:41], v[176:179], v[226:229], v[38:41]
	v_mfma_f32_16x16x32_bf16 v[34:37], v[192:195], v[226:229], v[34:37]
	v_mfma_f32_16x16x32_bf16 v[22:25], v[176:179], v[234:237], v[22:25]
	v_mfma_f32_16x16x32_bf16 v[18:21], v[192:195], v[234:237], v[18:21]
	v_mfma_f32_16x16x32_bf16 v[6:9], v[176:179], v[242:245], v[6:9]
	v_mfma_f32_16x16x32_bf16 v[2:5], v[192:195], v[242:245], v[2:5]
	v_mfma_f32_16x16x32_bf16 v[50:53], v[176:179], v[200:203], v[70:73]
	v_mfma_f32_16x16x32_bf16 v[54:57], v[192:195], v[200:203], v[66:69]
	v_mfma_f32_16x16x32_bf16 v[38:41], v[188:191], v[230:233], v[38:41]
	v_mfma_f32_16x16x32_bf16 v[34:37], v[196:199], v[230:233], v[34:37]
	v_mfma_f32_16x16x32_bf16 v[22:25], v[188:191], v[238:241], v[22:25]
	v_mfma_f32_16x16x32_bf16 v[18:21], v[196:199], v[238:241], v[18:21]
	v_mfma_f32_16x16x32_bf16 v[6:9], v[188:191], v[246:249], v[6:9]
	v_mfma_f32_16x16x32_bf16 v[2:5], v[196:199], v[246:249], v[2:5]
	v_mfma_f32_16x16x32_bf16 v[50:53], v[188:191], v[204:207], v[50:53]
	v_mfma_f32_16x16x32_bf16 v[54:57], v[196:199], v[204:207], v[54:57]
	s_setprio 0
	s_barrier
	s_add_i32 s47, 0, 0x18000
	v_add_u32_e32 v0, s47, v155
	s_add_i32 s54, 0, 0x1c000
	ds_read_b128 v[58:61], v0
	ds_read_b128 v[62:65], v0 offset:1024
	ds_read_b128 v[66:69], v0 offset:2048
	ds_read_b128 v[70:73], v0 offset:3072
	v_add_u32_e32 v0, s54, v155
	ds_read_b128 v[176:179], v0
	ds_read_b128 v[188:191], v0 offset:1024
	ds_read_b128 v[192:195], v0 offset:2048
	ds_read_b128 v[196:199], v0 offset:3072
	s_add_u32 s24, s24, 0x40000
	s_addc_u32 s25, s25, 0
	s_mov_b32 m0, s74
	v_lshl_add_u64 v[218:219], s[24:25], 0, v[146:147]
	ds_read_b128 v[200:203], v186 offset:32768
	ds_read_b128 v[204:207], v186 offset:33792
	ds_read_b128 v[226:229], v186 offset:34816
	ds_read_b128 v[230:233], v186 offset:35840
	ds_read_b128 v[234:237], v186 offset:36864
	ds_read_b128 v[238:241], v186 offset:37888
	ds_read_b128 v[242:245], v186 offset:38912
	ds_read_b128 v[246:249], v186 offset:39936
	global_load_lds_dwordx4 v[218:219], off
	v_lshl_add_u64 v[218:219], s[24:25], 0, v[148:149]
	s_mov_b32 m0, s75
	s_nop 0
	global_load_lds_dwordx4 v[218:219], off
	s_waitcnt vmcnt(8)
	s_waitcnt lgkmcnt(0)
	s_barrier
	s_setprio 1
	v_mfma_f32_16x16x32_bf16 v[142:145], v[58:61], v[200:203], v[142:145]
	v_mfma_f32_16x16x32_bf16 v[138:141], v[66:69], v[200:203], v[138:141]
	v_mfma_f32_16x16x32_bf16 v[126:129], v[58:61], v[226:229], v[126:129]
	v_mfma_f32_16x16x32_bf16 v[122:125], v[66:69], v[226:229], v[122:125]
	v_mfma_f32_16x16x32_bf16 v[110:113], v[58:61], v[234:237], v[110:113]
	v_mfma_f32_16x16x32_bf16 v[106:109], v[66:69], v[234:237], v[106:109]
	v_mfma_f32_16x16x32_bf16 v[94:97], v[58:61], v[242:245], v[94:97]
	v_mfma_f32_16x16x32_bf16 v[90:93], v[66:69], v[242:245], v[90:93]
	v_mfma_f32_16x16x32_bf16 v[142:145], v[62:65], v[204:207], v[142:145]
	v_mfma_f32_16x16x32_bf16 v[138:141], v[70:73], v[204:207], v[138:141]
	v_mfma_f32_16x16x32_bf16 v[126:129], v[62:65], v[230:233], v[126:129]
	v_mfma_f32_16x16x32_bf16 v[122:125], v[70:73], v[230:233], v[122:125]
	v_mfma_f32_16x16x32_bf16 v[110:113], v[62:65], v[238:241], v[110:113]
	v_mfma_f32_16x16x32_bf16 v[106:109], v[70:73], v[238:241], v[106:109]
	v_mfma_f32_16x16x32_bf16 v[94:97], v[62:65], v[246:249], v[94:97]
	v_mfma_f32_16x16x32_bf16 v[90:93], v[70:73], v[246:249], v[90:93]
	s_setprio 0
	s_setprio 1
	v_mfma_f32_16x16x32_bf16 v[134:137], v[176:179], v[200:203], v[134:137]
	v_mfma_f32_16x16x32_bf16 v[130:133], v[192:195], v[200:203], v[130:133]
	v_mfma_f32_16x16x32_bf16 v[118:121], v[176:179], v[226:229], v[118:121]
	v_mfma_f32_16x16x32_bf16 v[114:117], v[192:195], v[226:229], v[114:117]
	v_mfma_f32_16x16x32_bf16 v[102:105], v[176:179], v[234:237], v[102:105]
	v_mfma_f32_16x16x32_bf16 v[98:101], v[192:195], v[234:237], v[98:101]
	v_mfma_f32_16x16x32_bf16 v[86:89], v[176:179], v[242:245], v[86:89]
	v_mfma_f32_16x16x32_bf16 v[82:85], v[192:195], v[242:245], v[82:85]
	v_mfma_f32_16x16x32_bf16 v[134:137], v[188:191], v[204:207], v[134:137]
	v_mfma_f32_16x16x32_bf16 v[130:133], v[196:199], v[204:207], v[130:133]
	v_mfma_f32_16x16x32_bf16 v[118:121], v[188:191], v[230:233], v[118:121]
	v_mfma_f32_16x16x32_bf16 v[114:117], v[196:199], v[230:233], v[114:117]
	v_mfma_f32_16x16x32_bf16 v[102:105], v[188:191], v[238:241], v[102:105]
	v_mfma_f32_16x16x32_bf16 v[98:101], v[196:199], v[238:241], v[98:101]
	v_mfma_f32_16x16x32_bf16 v[86:89], v[188:191], v[246:249], v[86:89]
	v_mfma_f32_16x16x32_bf16 v[82:85], v[196:199], v[246:249], v[82:85]
	s_setprio 0
	s_barrier
	s_add_i32 s24, s47, s42
	v_lshl_add_u64 v[180:181], v[180:181], 0, s[44:45]
	s_mov_b32 m0, s24
	ds_read_b128 v[200:203], v186 offset:49152
	ds_read_b128 v[204:207], v186 offset:50176
	ds_read_b128 v[226:229], v186 offset:51200
	ds_read_b128 v[230:233], v186 offset:52224
	ds_read_b128 v[234:237], v186 offset:53248
	ds_read_b128 v[238:241], v186 offset:54272
	ds_read_b128 v[242:245], v186 offset:55296
	ds_read_b128 v[246:249], v186 offset:56320
	global_load_lds_dwordx4 v[180:181], off
	s_add_i32 m0, s24, 0x2000
	s_add_u32 s2, s2, 0x40080
	v_lshl_add_u64 v[180:181], v[222:223], 0, s[44:45]
	s_addc_u32 s3, s3, 0
	s_add_i32 s24, s54, s42
	global_load_lds_dwordx4 v[180:181], off
	v_lshl_add_u64 v[180:181], s[2:3], 0, v[146:147]
	s_mov_b32 m0, s24
	s_nop 0
	global_load_lds_dwordx4 v[180:181], off
	v_lshl_add_u64 v[180:181], s[2:3], 0, v[148:149]
	s_add_i32 m0, s24, 0x2000
	s_nop 0
	global_load_lds_dwordx4 v[180:181], off
	v_lshl_add_u64 v[180:181], v[224:225], 0, s[44:45]
	s_mov_b32 m0, s20
	s_nop 0
	global_load_lds_dwordx4 v[180:181], off
	v_lshl_add_u64 v[180:181], v[250:251], 0, s[44:45]
	s_mov_b32 m0, s21
	s_nop 0
	global_load_lds_dwordx4 v[180:181], off
	s_waitcnt vmcnt(8)
	s_waitcnt lgkmcnt(0)
	s_barrier
	s_setprio 1
	v_mfma_f32_16x16x32_bf16 v[78:81], v[58:61], v[200:203], v[78:81]
	v_mfma_f32_16x16x32_bf16 v[74:77], v[66:69], v[200:203], v[74:77]
	v_mfma_f32_16x16x32_bf16 v[46:49], v[58:61], v[226:229], v[46:49]
	v_mfma_f32_16x16x32_bf16 v[42:45], v[66:69], v[226:229], v[42:45]
	v_mfma_f32_16x16x32_bf16 v[30:33], v[58:61], v[234:237], v[30:33]
	v_mfma_f32_16x16x32_bf16 v[26:29], v[66:69], v[234:237], v[26:29]
	v_mfma_f32_16x16x32_bf16 v[14:17], v[58:61], v[242:245], v[14:17]
	v_mfma_f32_16x16x32_bf16 v[10:13], v[66:69], v[242:245], v[10:13]
	v_mfma_f32_16x16x32_bf16 v[78:81], v[62:65], v[204:207], v[78:81]
	v_mfma_f32_16x16x32_bf16 v[74:77], v[70:73], v[204:207], v[74:77]
	v_mfma_f32_16x16x32_bf16 v[46:49], v[62:65], v[230:233], v[46:49]
	v_mfma_f32_16x16x32_bf16 v[42:45], v[70:73], v[230:233], v[42:45]
	v_mfma_f32_16x16x32_bf16 v[30:33], v[62:65], v[238:241], v[30:33]
	v_mfma_f32_16x16x32_bf16 v[26:29], v[70:73], v[238:241], v[26:29]
	v_mfma_f32_16x16x32_bf16 v[14:17], v[62:65], v[246:249], v[14:17]
	v_mfma_f32_16x16x32_bf16 v[10:13], v[70:73], v[246:249], v[10:13]
	s_setprio 0
	s_setprio 1
	v_mfma_f32_16x16x32_bf16 v[50:53], v[176:179], v[200:203], v[50:53]
	v_mfma_f32_16x16x32_bf16 v[70:73], v[188:191], v[204:207], v[50:53]
	v_mfma_f32_16x16x32_bf16 v[50:53], v[192:195], v[200:203], v[54:57]
	v_mfma_f32_16x16x32_bf16 v[38:41], v[176:179], v[226:229], v[38:41]
	v_mfma_f32_16x16x32_bf16 v[34:37], v[192:195], v[226:229], v[34:37]
	v_mfma_f32_16x16x32_bf16 v[22:25], v[176:179], v[234:237], v[22:25]
	v_mfma_f32_16x16x32_bf16 v[18:21], v[192:195], v[234:237], v[18:21]
	v_mfma_f32_16x16x32_bf16 v[6:9], v[176:179], v[242:245], v[6:9]
	v_mfma_f32_16x16x32_bf16 v[2:5], v[192:195], v[242:245], v[2:5]
	v_mfma_f32_16x16x32_bf16 v[66:69], v[196:199], v[204:207], v[50:53]
	v_mfma_f32_16x16x32_bf16 v[38:41], v[188:191], v[230:233], v[38:41]
	v_mfma_f32_16x16x32_bf16 v[34:37], v[196:199], v[230:233], v[34:37]
	v_mfma_f32_16x16x32_bf16 v[22:25], v[188:191], v[238:241], v[22:25]
	v_mfma_f32_16x16x32_bf16 v[18:21], v[196:199], v[238:241], v[18:21]
	v_mfma_f32_16x16x32_bf16 v[6:9], v[188:191], v[246:249], v[6:9]
	v_mfma_f32_16x16x32_bf16 v[2:5], v[196:199], v[246:249], v[2:5]
	s_setprio 0
	s_barrier
	s_add_i32 s46, s46, 2
	s_add_u32 s14, s14, 0x100
	s_addc_u32 s15, s15, 0
	s_add_u32 s31, s31, 0x100
	s_addc_u32 s33, s33, 0
	s_cmp_gt_u32 s46, 13
	s_cbranch_scc0 .LBB0_176
	s_and_b64 vcc, exec, s[22:23]
	s_cbranch_vccz .LBB0_179
	s_barrier

.LBB0_650:
	s_add_u32 s2, s4, 0x100
	s_addc_u32 s3, s5, 0
	s_add_i32 s49, 0, 0x10000
	s_cmp_eq_u32 s48, 12
	s_cselect_b32 s29, s17, s3
	s_cselect_b32 s28, s25, s2
	v_add_u32_e32 v0, s49, v135
	s_cselect_b32 s27, s15, s47
	s_cselect_b32 s26, s42, s46
	s_add_i32 s50, 0, 0x14000
	ds_read_b128 v[146:149], v0
	ds_read_b128 v[150:153], v0 offset:1024
	ds_read_b128 v[154:157], v0 offset:2048
	ds_read_b128 v[158:161], v0 offset:3072
	v_add_u32_e32 v0, s50, v135
	ds_read_b128 v[162:165], v0
	ds_read_b128 v[166:169], v0 offset:1024
	ds_read_b128 v[170:173], v0 offset:2048
	ds_read_b128 v[174:177], v0 offset:3072
	v_lshl_add_u64 v[142:143], s[4:5], 0, v[138:139]
	s_add_i32 m0, s23, 0xc000
	ds_read_b128 v[178:181], v144
	ds_read_b128 v[182:185], v144 offset:1024
	ds_read_b128 v[186:189], v144 offset:2048
	ds_read_b128 v[190:193], v144 offset:3072
	ds_read_b128 v[194:197], v144 offset:4096
	ds_read_b128 v[198:201], v144 offset:5120
	ds_read_b128 v[202:205], v144 offset:6144
	ds_read_b128 v[222:225], v144 offset:7168
	global_load_lds_dwordx4 v[142:143], off
	v_lshl_add_u64 v[142:143], s[4:5], 0, v[140:141]
	s_add_i32 m0, s23, 0xe000
	s_nop 0
	global_load_lds_dwordx4 v[142:143], off
	s_waitcnt vmcnt(8)
	s_waitcnt lgkmcnt(0)
	s_barrier
	s_setprio 1
	v_mfma_f32_16x16x32_bf16 v[126:129], v[146:149], v[178:181], v[126:129]
	v_mfma_f32_16x16x32_bf16 v[122:125], v[154:157], v[178:181], v[122:125]
	v_mfma_f32_16x16x32_bf16 v[110:113], v[146:149], v[186:189], v[110:113]
	v_mfma_f32_16x16x32_bf16 v[106:109], v[154:157], v[186:189], v[106:109]
	v_mfma_f32_16x16x32_bf16 v[94:97], v[146:149], v[194:197], v[94:97]
	v_mfma_f32_16x16x32_bf16 v[90:93], v[154:157], v[194:197], v[90:93]
	v_mfma_f32_16x16x32_bf16 v[78:81], v[146:149], v[202:205], v[78:81]
	v_mfma_f32_16x16x32_bf16 v[74:77], v[154:157], v[202:205], v[74:77]
	v_mfma_f32_16x16x32_bf16 v[126:129], v[150:153], v[182:185], v[126:129]
	v_mfma_f32_16x16x32_bf16 v[122:125], v[158:161], v[182:185], v[122:125]
	v_mfma_f32_16x16x32_bf16 v[110:113], v[150:153], v[190:193], v[110:113]
	v_mfma_f32_16x16x32_bf16 v[106:109], v[158:161], v[190:193], v[106:109]
	v_mfma_f32_16x16x32_bf16 v[94:97], v[150:153], v[198:201], v[94:97]
	v_mfma_f32_16x16x32_bf16 v[90:93], v[158:161], v[198:201], v[90:93]
	v_mfma_f32_16x16x32_bf16 v[78:81], v[150:153], v[222:225], v[78:81]
	v_mfma_f32_16x16x32_bf16 v[74:77], v[158:161], v[222:225], v[74:77]
	s_setprio 0
	s_setprio 1
	v_mfma_f32_16x16x32_bf16 v[118:121], v[162:165], v[178:181], v[118:121]
	v_mfma_f32_16x16x32_bf16 v[114:117], v[170:173], v[178:181], v[114:117]
	v_mfma_f32_16x16x32_bf16 v[102:105], v[162:165], v[186:189], v[102:105]
	v_mfma_f32_16x16x32_bf16 v[98:101], v[170:173], v[186:189], v[98:101]
	v_mfma_f32_16x16x32_bf16 v[86:89], v[162:165], v[194:197], v[86:89]
	v_mfma_f32_16x16x32_bf16 v[82:85], v[170:173], v[194:197], v[82:85]
	v_mfma_f32_16x16x32_bf16 v[70:73], v[162:165], v[202:205], v[70:73]
	v_mfma_f32_16x16x32_bf16 v[66:69], v[170:173], v[202:205], v[66:69]
	v_mfma_f32_16x16x32_bf16 v[118:121], v[166:169], v[182:185], v[118:121]
	v_mfma_f32_16x16x32_bf16 v[114:117], v[174:177], v[182:185], v[114:117]
	v_mfma_f32_16x16x32_bf16 v[102:105], v[166:169], v[190:193], v[102:105]
	v_mfma_f32_16x16x32_bf16 v[98:101], v[174:177], v[190:193], v[98:101]
	v_mfma_f32_16x16x32_bf16 v[86:89], v[166:169], v[198:201], v[86:89]
	v_mfma_f32_16x16x32_bf16 v[82:85], v[174:177], v[198:201], v[82:85]
	v_mfma_f32_16x16x32_bf16 v[70:73], v[166:169], v[222:225], v[70:73]
	v_mfma_f32_16x16x32_bf16 v[66:69], v[174:177], v[222:225], v[66:69]
	s_setprio 0
	s_barrier
	s_add_i32 s4, s49, s30
	v_lshl_add_u64 v[142:143], s[26:27], 0, v[130:131]
	s_mov_b32 m0, s4
	ds_read_b128 v[178:181], v144 offset:16384
	ds_read_b128 v[182:185], v144 offset:17408
	ds_read_b128 v[186:189], v144 offset:18432
	ds_read_b128 v[190:193], v144 offset:19456
	ds_read_b128 v[194:197], v144 offset:20480
	ds_read_b128 v[198:201], v144 offset:21504
	ds_read_b128 v[202:205], v144 offset:22528
	ds_read_b128 v[222:225], v144 offset:23552
	global_load_lds_dwordx4 v[142:143], off
	s_add_i32 m0, s4, 0x2000
	s_add_u32 s4, s26, 0x40000
	v_lshl_add_u64 v[206:207], s[26:27], 0, v[132:133]
	s_addc_u32 s5, s27, 0
	s_add_i32 s49, s50, s30
	global_load_lds_dwordx4 v[206:207], off
	v_lshl_add_u64 v[218:219], s[4:5], 0, v[130:131]
	s_mov_b32 m0, s49
	v_lshl_add_u64 v[226:227], s[28:29], 0, v[132:133]
	global_load_lds_dwordx4 v[218:219], off
	v_lshl_add_u64 v[218:219], s[4:5], 0, v[132:133]
	s_add_i32 m0, s49, 0x2000
	s_nop 0
	global_load_lds_dwordx4 v[218:219], off
	v_lshl_add_u64 v[218:219], s[28:29], 0, v[130:131]
	s_mov_b32 m0, s23
	s_nop 0
	global_load_lds_dwordx4 v[218:219], off
	s_mov_b32 m0, s31
	s_nop 0
	global_load_lds_dwordx4 v[226:227], off
	s_waitcnt vmcnt(8)
	s_waitcnt lgkmcnt(0)
	s_barrier
	s_setprio 1
	v_mfma_f32_16x16x32_bf16 v[62:65], v[146:149], v[178:181], v[62:65]
	v_mfma_f32_16x16x32_bf16 v[58:61], v[154:157], v[178:181], v[58:61]
	v_mfma_f32_16x16x32_bf16 v[46:49], v[146:149], v[186:189], v[46:49]
	v_mfma_f32_16x16x32_bf16 v[42:45], v[154:157], v[186:189], v[42:45]
	v_mfma_f32_16x16x32_bf16 v[30:33], v[146:149], v[194:197], v[30:33]
	v_mfma_f32_16x16x32_bf16 v[26:29], v[154:157], v[194:197], v[26:29]
	v_mfma_f32_16x16x32_bf16 v[14:17], v[146:149], v[202:205], v[14:17]
	v_mfma_f32_16x16x32_bf16 v[10:13], v[154:157], v[202:205], v[10:13]
	v_mfma_f32_16x16x32_bf16 v[62:65], v[150:153], v[182:185], v[62:65]
	v_mfma_f32_16x16x32_bf16 v[58:61], v[158:161], v[182:185], v[58:61]
	v_mfma_f32_16x16x32_bf16 v[46:49], v[150:153], v[190:193], v[46:49]
	v_mfma_f32_16x16x32_bf16 v[42:45], v[158:161], v[190:193], v[42:45]
	v_mfma_f32_16x16x32_bf16 v[30:33], v[150:153], v[198:201], v[30:33]
	v_mfma_f32_16x16x32_bf16 v[26:29], v[158:161], v[198:201], v[26:29]
	v_mfma_f32_16x16x32_bf16 v[14:17], v[150:153], v[222:225], v[14:17]
	v_mfma_f32_16x16x32_bf16 v[10:13], v[158:161], v[222:225], v[10:13]
	s_setprio 0
	s_setprio 1
	v_mfma_f32_16x16x32_bf16 v[54:57], v[162:165], v[178:181], v[54:57]
	v_mfma_f32_16x16x32_bf16 v[50:53], v[170:173], v[178:181], v[50:53]
	v_mfma_f32_16x16x32_bf16 v[38:41], v[162:165], v[186:189], v[38:41]
	v_mfma_f32_16x16x32_bf16 v[34:37], v[170:173], v[186:189], v[34:37]
	v_mfma_f32_16x16x32_bf16 v[22:25], v[162:165], v[194:197], v[22:25]
	v_mfma_f32_16x16x32_bf16 v[18:21], v[170:173], v[194:197], v[18:21]
	v_mfma_f32_16x16x32_bf16 v[6:9], v[162:165], v[202:205], v[6:9]
	v_mfma_f32_16x16x32_bf16 v[2:5], v[170:173], v[202:205], v[2:5]
	v_mfma_f32_16x16x32_bf16 v[54:57], v[166:169], v[182:185], v[54:57]
	v_mfma_f32_16x16x32_bf16 v[50:53], v[174:177], v[182:185], v[50:53]
	v_mfma_f32_16x16x32_bf16 v[38:41], v[166:169], v[190:193], v[38:41]
	v_mfma_f32_16x16x32_bf16 v[34:37], v[174:177], v[190:193], v[34:37]
	v_mfma_f32_16x16x32_bf16 v[22:25], v[166:169], v[198:201], v[22:25]
	v_mfma_f32_16x16x32_bf16 v[18:21], v[174:177], v[198:201], v[18:21]
	v_mfma_f32_16x16x32_bf16 v[6:9], v[166:169], v[222:225], v[6:9]
	v_mfma_f32_16x16x32_bf16 v[2:5], v[174:177], v[222:225], v[2:5]
	s_setprio 0
	s_barrier
	s_add_i32 s49, 0, 0x18000
	v_add_u32_e32 v0, s49, v135
	s_add_i32 s50, 0, 0x1c000
	ds_read_b128 v[146:149], v0
	ds_read_b128 v[150:153], v0 offset:1024
	ds_read_b128 v[154:157], v0 offset:2048
	ds_read_b128 v[158:161], v0 offset:3072
	v_add_u32_e32 v0, s50, v135
	ds_read_b128 v[162:165], v0
	ds_read_b128 v[166:169], v0 offset:1024
	ds_read_b128 v[170:173], v0 offset:2048
	ds_read_b128 v[174:177], v0 offset:3072
	s_add_u32 s4, s28, 0x40000
	s_addc_u32 s5, s29, 0
	s_mov_b32 m0, s33
	v_lshl_add_u64 v[228:229], s[4:5], 0, v[130:131]
	ds_read_b128 v[178:181], v144 offset:32768
	ds_read_b128 v[182:185], v144 offset:33792
	ds_read_b128 v[186:189], v144 offset:34816
	ds_read_b128 v[190:193], v144 offset:35840
	ds_read_b128 v[194:197], v144 offset:36864
	ds_read_b128 v[198:201], v144 offset:37888
	ds_read_b128 v[202:205], v144 offset:38912
	ds_read_b128 v[222:225], v144 offset:39936
	global_load_lds_dwordx4 v[228:229], off
	v_lshl_add_u64 v[228:229], s[4:5], 0, v[132:133]
	s_mov_b32 m0, s34
	s_nop 0
	global_load_lds_dwordx4 v[228:229], off
	s_waitcnt vmcnt(8)
	s_waitcnt lgkmcnt(0)
	s_barrier
	s_setprio 1
	v_mfma_f32_16x16x32_bf16 v[126:129], v[146:149], v[178:181], v[126:129]
	v_mfma_f32_16x16x32_bf16 v[122:125], v[154:157], v[178:181], v[122:125]
	v_mfma_f32_16x16x32_bf16 v[110:113], v[146:149], v[186:189], v[110:113]
	v_mfma_f32_16x16x32_bf16 v[106:109], v[154:157], v[186:189], v[106:109]
	v_mfma_f32_16x16x32_bf16 v[94:97], v[146:149], v[194:197], v[94:97]
	v_mfma_f32_16x16x32_bf16 v[90:93], v[154:157], v[194:197], v[90:93]
	v_mfma_f32_16x16x32_bf16 v[78:81], v[146:149], v[202:205], v[78:81]
	v_mfma_f32_16x16x32_bf16 v[74:77], v[154:157], v[202:205], v[74:77]
	v_mfma_f32_16x16x32_bf16 v[126:129], v[150:153], v[182:185], v[126:129]
	v_mfma_f32_16x16x32_bf16 v[122:125], v[158:161], v[182:185], v[122:125]
	v_mfma_f32_16x16x32_bf16 v[110:113], v[150:153], v[190:193], v[110:113]
	v_mfma_f32_16x16x32_bf16 v[106:109], v[158:161], v[190:193], v[106:109]
	v_mfma_f32_16x16x32_bf16 v[94:97], v[150:153], v[198:201], v[94:97]
	v_mfma_f32_16x16x32_bf16 v[90:93], v[158:161], v[198:201], v[90:93]
	v_mfma_f32_16x16x32_bf16 v[78:81], v[150:153], v[222:225], v[78:81]
	v_mfma_f32_16x16x32_bf16 v[74:77], v[158:161], v[222:225], v[74:77]
	s_setprio 0
	s_setprio 1
	v_mfma_f32_16x16x32_bf16 v[118:121], v[162:165], v[178:181], v[118:121]
	v_mfma_f32_16x16x32_bf16 v[114:117], v[170:173], v[178:181], v[114:117]
	v_mfma_f32_16x16x32_bf16 v[102:105], v[162:165], v[186:189], v[102:105]
	v_mfma_f32_16x16x32_bf16 v[98:101], v[170:173], v[186:189], v[98:101]
	v_mfma_f32_16x16x32_bf16 v[86:89], v[162:165], v[194:197], v[86:89]
	v_mfma_f32_16x16x32_bf16 v[82:85], v[170:173], v[194:197], v[82:85]
	v_mfma_f32_16x16x32_bf16 v[70:73], v[162:165], v[202:205], v[70:73]
	v_mfma_f32_16x16x32_bf16 v[66:69], v[170:173], v[202:205], v[66:69]
	v_mfma_f32_16x16x32_bf16 v[118:121], v[166:169], v[182:185], v[118:121]
	v_mfma_f32_16x16x32_bf16 v[114:117], v[174:177], v[182:185], v[114:117]
	v_mfma_f32_16x16x32_bf16 v[102:105], v[166:169], v[190:193], v[102:105]
	v_mfma_f32_16x16x32_bf16 v[98:101], v[174:177], v[190:193], v[98:101]
	v_mfma_f32_16x16x32_bf16 v[86:89], v[166:169], v[198:201], v[86:89]
	v_mfma_f32_16x16x32_bf16 v[82:85], v[174:177], v[198:201], v[82:85]
	v_mfma_f32_16x16x32_bf16 v[70:73], v[166:169], v[222:225], v[70:73]
	v_mfma_f32_16x16x32_bf16 v[66:69], v[174:177], v[222:225], v[66:69]
	s_setprio 0
	s_barrier
	s_add_i32 s4, s49, s30
	v_lshl_add_u64 v[142:143], v[142:143], 0, s[44:45]
	s_mov_b32 m0, s4
	ds_read_b128 v[178:181], v144 offset:49152
	ds_read_b128 v[182:185], v144 offset:50176
	ds_read_b128 v[186:189], v144 offset:51200
	ds_read_b128 v[190:193], v144 offset:52224
	ds_read_b128 v[194:197], v144 offset:53248
	ds_read_b128 v[198:201], v144 offset:54272
	ds_read_b128 v[202:205], v144 offset:55296
	ds_read_b128 v[222:225], v144 offset:56320
	global_load_lds_dwordx4 v[142:143], off
	s_add_i32 m0, s4, 0x2000
	s_add_u32 s4, s26, 0x40080
	v_lshl_add_u64 v[142:143], v[206:207], 0, s[44:45]
	s_addc_u32 s5, s27, 0
	s_add_i32 s26, s50, s30
	global_load_lds_dwordx4 v[142:143], off
	v_lshl_add_u64 v[142:143], s[4:5], 0, v[130:131]
	s_mov_b32 m0, s26
	s_nop 0
	global_load_lds_dwordx4 v[142:143], off
	v_lshl_add_u64 v[142:143], s[4:5], 0, v[132:133]
	s_add_i32 m0, s26, 0x2000
	s_nop 0
	global_load_lds_dwordx4 v[142:143], off
	v_lshl_add_u64 v[142:143], v[218:219], 0, s[44:45]
	s_mov_b32 m0, s37
	s_nop 0
	global_load_lds_dwordx4 v[142:143], off
	v_lshl_add_u64 v[142:143], v[226:227], 0, s[44:45]
	s_mov_b32 m0, s38
	s_nop 0
	global_load_lds_dwordx4 v[142:143], off
	s_waitcnt vmcnt(8)
	s_waitcnt lgkmcnt(0)
	s_barrier
	s_setprio 1
	v_mfma_f32_16x16x32_bf16 v[62:65], v[146:149], v[178:181], v[62:65]
	v_mfma_f32_16x16x32_bf16 v[58:61], v[154:157], v[178:181], v[58:61]
	v_mfma_f32_16x16x32_bf16 v[46:49], v[146:149], v[186:189], v[46:49]
	v_mfma_f32_16x16x32_bf16 v[42:45], v[154:157], v[186:189], v[42:45]
	v_mfma_f32_16x16x32_bf16 v[30:33], v[146:149], v[194:197], v[30:33]
	v_mfma_f32_16x16x32_bf16 v[26:29], v[154:157], v[194:197], v[26:29]
	v_mfma_f32_16x16x32_bf16 v[14:17], v[146:149], v[202:205], v[14:17]
	v_mfma_f32_16x16x32_bf16 v[10:13], v[154:157], v[202:205], v[10:13]
	v_mfma_f32_16x16x32_bf16 v[62:65], v[150:153], v[182:185], v[62:65]
	v_mfma_f32_16x16x32_bf16 v[58:61], v[158:161], v[182:185], v[58:61]
	v_mfma_f32_16x16x32_bf16 v[46:49], v[150:153], v[190:193], v[46:49]
	v_mfma_f32_16x16x32_bf16 v[42:45], v[158:161], v[190:193], v[42:45]
	v_mfma_f32_16x16x32_bf16 v[30:33], v[150:153], v[198:201], v[30:33]
	v_mfma_f32_16x16x32_bf16 v[26:29], v[158:161], v[198:201], v[26:29]
	v_mfma_f32_16x16x32_bf16 v[14:17], v[150:153], v[222:225], v[14:17]
	v_mfma_f32_16x16x32_bf16 v[10:13], v[158:161], v[222:225], v[10:13]
	s_setprio 0
	s_setprio 1
	v_mfma_f32_16x16x32_bf16 v[54:57], v[162:165], v[178:181], v[54:57]
	v_mfma_f32_16x16x32_bf16 v[50:53], v[170:173], v[178:181], v[50:53]
	v_mfma_f32_16x16x32_bf16 v[38:41], v[162:165], v[186:189], v[38:41]
	v_mfma_f32_16x16x32_bf16 v[34:37], v[170:173], v[186:189], v[34:37]
	v_mfma_f32_16x16x32_bf16 v[22:25], v[162:165], v[194:197], v[22:25]
	v_mfma_f32_16x16x32_bf16 v[18:21], v[170:173], v[194:197], v[18:21]
	v_mfma_f32_16x16x32_bf16 v[6:9], v[162:165], v[202:205], v[6:9]
	v_mfma_f32_16x16x32_bf16 v[2:5], v[170:173], v[202:205], v[2:5]
	v_mfma_f32_16x16x32_bf16 v[54:57], v[166:169], v[182:185], v[54:57]
	v_mfma_f32_16x16x32_bf16 v[50:53], v[174:177], v[182:185], v[50:53]
	v_mfma_f32_16x16x32_bf16 v[38:41], v[166:169], v[190:193], v[38:41]
	v_mfma_f32_16x16x32_bf16 v[34:37], v[174:177], v[190:193], v[34:37]
	v_mfma_f32_16x16x32_bf16 v[22:25], v[166:169], v[198:201], v[22:25]
	v_mfma_f32_16x16x32_bf16 v[18:21], v[174:177], v[198:201], v[18:21]
	v_mfma_f32_16x16x32_bf16 v[6:9], v[166:169], v[222:225], v[6:9]
	v_mfma_f32_16x16x32_bf16 v[2:5], v[174:177], v[222:225], v[2:5]
	s_setprio 0
	s_barrier
	s_add_i32 s48, s48, 2
	s_add_u32 s46, s46, 0x100
	s_addc_u32 s47, s47, 0
	s_cmp_gt_u32 s48, 13
	s_mov_b64 s[4:5], s[2:3]
	s_cbranch_scc0 .LBB0_650
	s_and_b64 vcc, exec, s[12:13]
	s_cbranch_vccz .LBB0_653
	s_barrier

.LBB0_783:
	s_add_u32 s2, s4, 0xfffc0080
	s_addc_u32 s3, s5, -1
	s_add_i32 s48, 0, 0x10000
	s_cmp_eq_u32 s47, 12
	s_cselect_b32 s27, s17, s3
	s_cselect_b32 s26, s25, s2
	s_cselect_b32 s3, s15, s46
	s_cselect_b32 s2, s41, s42
	s_add_i32 s50, 0, 0x14000
	v_add_u32_e32 v154, s48, v140
	v_add_u32_e32 v170, s50, v140
	ds_read_b128 v[142:145], v154
	ds_read_b128 v[146:149], v154 offset:1024
	ds_read_b128 v[150:153], v154 offset:2048
	ds_read_b128 v[154:157], v154 offset:3072
	ds_read_b128 v[158:161], v170
	ds_read_b128 v[162:165], v170 offset:1024
	ds_read_b128 v[166:169], v170 offset:2048
	ds_read_b128 v[170:173], v170 offset:3072
	v_lshl_add_u64 v[206:207], s[4:5], 0, v[136:137]
	s_add_i32 m0, s23, 0xc000
	ds_read_b128 v[174:177], v141
	ds_read_b128 v[178:181], v141 offset:1024
	ds_read_b128 v[182:185], v141 offset:2048
	ds_read_b128 v[186:189], v141 offset:3072
	ds_read_b128 v[190:193], v141 offset:4096
	ds_read_b128 v[194:197], v141 offset:5120
	ds_read_b128 v[198:201], v141 offset:6144
	ds_read_b128 v[202:205], v141 offset:7168
	global_load_lds_dwordx4 v[206:207], off
	v_lshl_add_u64 v[206:207], s[4:5], 0, v[138:139]
	s_add_i32 m0, s23, 0xe000
	s_nop 0
	global_load_lds_dwordx4 v[206:207], off
	s_waitcnt vmcnt(8)
	s_waitcnt lgkmcnt(0)
	s_barrier
	s_setprio 1
	v_mfma_f32_16x16x32_bf16 v[122:125], v[142:145], v[174:177], v[122:125]
	v_mfma_f32_16x16x32_bf16 v[114:117], v[150:153], v[174:177], v[114:117]
	v_mfma_f32_16x16x32_bf16 v[106:109], v[142:145], v[182:185], v[106:109]
	v_mfma_f32_16x16x32_bf16 v[98:101], v[150:153], v[182:185], v[98:101]
	v_mfma_f32_16x16x32_bf16 v[90:93], v[142:145], v[190:193], v[90:93]
	v_mfma_f32_16x16x32_bf16 v[82:85], v[150:153], v[190:193], v[82:85]
	v_mfma_f32_16x16x32_bf16 v[74:77], v[142:145], v[198:201], v[74:77]
	v_mfma_f32_16x16x32_bf16 v[66:69], v[150:153], v[198:201], v[66:69]
	v_mfma_f32_16x16x32_bf16 v[122:125], v[146:149], v[178:181], v[122:125]
	v_mfma_f32_16x16x32_bf16 v[114:117], v[154:157], v[178:181], v[114:117]
	v_mfma_f32_16x16x32_bf16 v[106:109], v[146:149], v[186:189], v[106:109]
	v_mfma_f32_16x16x32_bf16 v[98:101], v[154:157], v[186:189], v[98:101]
	v_mfma_f32_16x16x32_bf16 v[90:93], v[146:149], v[194:197], v[90:93]
	v_mfma_f32_16x16x32_bf16 v[82:85], v[154:157], v[194:197], v[82:85]
	v_mfma_f32_16x16x32_bf16 v[74:77], v[146:149], v[202:205], v[74:77]
	v_mfma_f32_16x16x32_bf16 v[66:69], v[154:157], v[202:205], v[66:69]
	s_setprio 0
	s_setprio 1
	v_mfma_f32_16x16x32_bf16 v[126:129], v[158:161], v[174:177], v[126:129]
	v_mfma_f32_16x16x32_bf16 v[118:121], v[166:169], v[174:177], v[118:121]
	v_mfma_f32_16x16x32_bf16 v[110:113], v[158:161], v[182:185], v[110:113]
	v_mfma_f32_16x16x32_bf16 v[102:105], v[166:169], v[182:185], v[102:105]
	v_mfma_f32_16x16x32_bf16 v[94:97], v[158:161], v[190:193], v[94:97]
	v_mfma_f32_16x16x32_bf16 v[86:89], v[166:169], v[190:193], v[86:89]
	v_mfma_f32_16x16x32_bf16 v[78:81], v[158:161], v[198:201], v[78:81]
	v_mfma_f32_16x16x32_bf16 v[70:73], v[166:169], v[198:201], v[70:73]
	v_mfma_f32_16x16x32_bf16 v[126:129], v[162:165], v[178:181], v[126:129]
	v_mfma_f32_16x16x32_bf16 v[118:121], v[170:173], v[178:181], v[118:121]
	v_mfma_f32_16x16x32_bf16 v[110:113], v[162:165], v[186:189], v[110:113]
	v_mfma_f32_16x16x32_bf16 v[102:105], v[170:173], v[186:189], v[102:105]
	v_mfma_f32_16x16x32_bf16 v[94:97], v[162:165], v[194:197], v[94:97]
	v_mfma_f32_16x16x32_bf16 v[86:89], v[170:173], v[194:197], v[86:89]
	v_mfma_f32_16x16x32_bf16 v[78:81], v[162:165], v[202:205], v[78:81]
	v_mfma_f32_16x16x32_bf16 v[70:73], v[170:173], v[202:205], v[70:73]
	s_setprio 0
	s_barrier
	s_add_i32 s48, s48, s28
	v_lshl_add_u64 v[206:207], s[2:3], 0, v[132:133]
	s_mov_b32 m0, s48
	ds_read_b128 v[174:177], v141 offset:16384
	ds_read_b128 v[178:181], v141 offset:17408
	ds_read_b128 v[182:185], v141 offset:18432
	ds_read_b128 v[186:189], v141 offset:19456
	ds_read_b128 v[190:193], v141 offset:20480
	ds_read_b128 v[194:197], v141 offset:21504
	ds_read_b128 v[198:201], v141 offset:22528
	ds_read_b128 v[202:205], v141 offset:23552
	global_load_lds_dwordx4 v[206:207], off
	s_add_i32 m0, s48, 0x2000
	s_add_u32 s48, s2, 0x40000
	v_lshl_add_u64 v[218:219], s[2:3], 0, v[130:131]
	s_addc_u32 s49, s3, 0
	s_add_i32 s50, s50, s28
	global_load_lds_dwordx4 v[218:219], off
	v_lshl_add_u64 v[222:223], s[48:49], 0, v[132:133]
	s_mov_b32 m0, s50
	v_lshl_add_u64 v[224:225], s[26:27], 0, v[130:131]
	global_load_lds_dwordx4 v[222:223], off
	v_lshl_add_u64 v[222:223], s[48:49], 0, v[130:131]
	s_add_i32 m0, s50, 0x2000
	s_nop 0
	global_load_lds_dwordx4 v[222:223], off
	v_lshl_add_u64 v[222:223], s[26:27], 0, v[132:133]
	s_mov_b32 m0, s23
	s_nop 0
	global_load_lds_dwordx4 v[222:223], off
	s_mov_b32 m0, s31
	s_nop 0
	global_load_lds_dwordx4 v[224:225], off
	s_waitcnt vmcnt(8)
	s_waitcnt lgkmcnt(0)
	s_barrier
	s_setprio 1
	v_mfma_f32_16x16x32_bf16 v[58:61], v[142:145], v[174:177], v[58:61]
	v_mfma_f32_16x16x32_bf16 v[50:53], v[150:153], v[174:177], v[50:53]
	v_mfma_f32_16x16x32_bf16 v[42:45], v[142:145], v[182:185], v[42:45]
	v_mfma_f32_16x16x32_bf16 v[34:37], v[150:153], v[182:185], v[34:37]
	v_mfma_f32_16x16x32_bf16 v[26:29], v[142:145], v[190:193], v[26:29]
	v_mfma_f32_16x16x32_bf16 v[18:21], v[150:153], v[190:193], v[18:21]
	v_mfma_f32_16x16x32_bf16 v[10:13], v[142:145], v[198:201], v[10:13]
	v_mfma_f32_16x16x32_bf16 v[2:5], v[150:153], v[198:201], v[2:5]
	v_mfma_f32_16x16x32_bf16 v[58:61], v[146:149], v[178:181], v[58:61]
	v_mfma_f32_16x16x32_bf16 v[50:53], v[154:157], v[178:181], v[50:53]
	v_mfma_f32_16x16x32_bf16 v[42:45], v[146:149], v[186:189], v[42:45]
	v_mfma_f32_16x16x32_bf16 v[34:37], v[154:157], v[186:189], v[34:37]
	v_mfma_f32_16x16x32_bf16 v[26:29], v[146:149], v[194:197], v[26:29]
	v_mfma_f32_16x16x32_bf16 v[18:21], v[154:157], v[194:197], v[18:21]
	v_mfma_f32_16x16x32_bf16 v[10:13], v[146:149], v[202:205], v[10:13]
	v_mfma_f32_16x16x32_bf16 v[2:5], v[154:157], v[202:205], v[2:5]
	s_setprio 0
	s_setprio 1
	v_mfma_f32_16x16x32_bf16 v[62:65], v[158:161], v[174:177], v[62:65]
	v_mfma_f32_16x16x32_bf16 v[54:57], v[166:169], v[174:177], v[54:57]
	v_mfma_f32_16x16x32_bf16 v[46:49], v[158:161], v[182:185], v[46:49]
	v_mfma_f32_16x16x32_bf16 v[38:41], v[166:169], v[182:185], v[38:41]
	v_mfma_f32_16x16x32_bf16 v[30:33], v[158:161], v[190:193], v[30:33]
	v_mfma_f32_16x16x32_bf16 v[22:25], v[166:169], v[190:193], v[22:25]
	v_mfma_f32_16x16x32_bf16 v[14:17], v[158:161], v[198:201], v[14:17]
	v_mfma_f32_16x16x32_bf16 v[6:9], v[166:169], v[198:201], v[6:9]
	v_mfma_f32_16x16x32_bf16 v[62:65], v[162:165], v[178:181], v[62:65]
	v_mfma_f32_16x16x32_bf16 v[54:57], v[170:173], v[178:181], v[54:57]
	v_mfma_f32_16x16x32_bf16 v[46:49], v[162:165], v[186:189], v[46:49]
	v_mfma_f32_16x16x32_bf16 v[38:41], v[170:173], v[186:189], v[38:41]
	v_mfma_f32_16x16x32_bf16 v[30:33], v[162:165], v[194:197], v[30:33]
	v_mfma_f32_16x16x32_bf16 v[22:25], v[170:173], v[194:197], v[22:25]
	v_mfma_f32_16x16x32_bf16 v[14:17], v[162:165], v[202:205], v[14:17]
	v_mfma_f32_16x16x32_bf16 v[6:9], v[170:173], v[202:205], v[6:9]
	s_setprio 0
	s_barrier
	s_add_i32 s48, 0, 0x18000
	s_add_i32 s49, 0, 0x1c000
	v_add_u32_e32 v154, s48, v140
	v_add_u32_e32 v170, s49, v140
	ds_read_b128 v[142:145], v154
	ds_read_b128 v[146:149], v154 offset:1024
	ds_read_b128 v[150:153], v154 offset:2048
	ds_read_b128 v[154:157], v154 offset:3072
	ds_read_b128 v[158:161], v170
	ds_read_b128 v[162:165], v170 offset:1024
	ds_read_b128 v[166:169], v170 offset:2048
	ds_read_b128 v[170:173], v170 offset:3072
	s_add_u32 s26, s26, 0x40000
	s_addc_u32 s27, s27, 0
	s_mov_b32 m0, s33
	v_lshl_add_u64 v[226:227], s[26:27], 0, v[132:133]
	ds_read_b128 v[174:177], v141 offset:32768
	ds_read_b128 v[178:181], v141 offset:33792
	ds_read_b128 v[182:185], v141 offset:34816
	ds_read_b128 v[186:189], v141 offset:35840
	ds_read_b128 v[190:193], v141 offset:36864
	ds_read_b128 v[194:197], v141 offset:37888
	ds_read_b128 v[198:201], v141 offset:38912
	ds_read_b128 v[202:205], v141 offset:39936
	global_load_lds_dwordx4 v[226:227], off
	v_lshl_add_u64 v[226:227], s[26:27], 0, v[130:131]
	s_mov_b32 m0, s34
	s_nop 0
	global_load_lds_dwordx4 v[226:227], off
	s_waitcnt vmcnt(8)
	s_waitcnt lgkmcnt(0)
	s_barrier
	s_setprio 1
	v_mfma_f32_16x16x32_bf16 v[122:125], v[142:145], v[174:177], v[122:125]
	v_mfma_f32_16x16x32_bf16 v[114:117], v[150:153], v[174:177], v[114:117]
	v_mfma_f32_16x16x32_bf16 v[106:109], v[142:145], v[182:185], v[106:109]
	v_mfma_f32_16x16x32_bf16 v[98:101], v[150:153], v[182:185], v[98:101]
	v_mfma_f32_16x16x32_bf16 v[90:93], v[142:145], v[190:193], v[90:93]
	v_mfma_f32_16x16x32_bf16 v[82:85], v[150:153], v[190:193], v[82:85]
	v_mfma_f32_16x16x32_bf16 v[74:77], v[142:145], v[198:201], v[74:77]
	v_mfma_f32_16x16x32_bf16 v[66:69], v[150:153], v[198:201], v[66:69]
	v_mfma_f32_16x16x32_bf16 v[122:125], v[146:149], v[178:181], v[122:125]
	v_mfma_f32_16x16x32_bf16 v[114:117], v[154:157], v[178:181], v[114:117]
	v_mfma_f32_16x16x32_bf16 v[106:109], v[146:149], v[186:189], v[106:109]
	v_mfma_f32_16x16x32_bf16 v[98:101], v[154:157], v[186:189], v[98:101]
	v_mfma_f32_16x16x32_bf16 v[90:93], v[146:149], v[194:197], v[90:93]
	v_mfma_f32_16x16x32_bf16 v[82:85], v[154:157], v[194:197], v[82:85]
	v_mfma_f32_16x16x32_bf16 v[74:77], v[146:149], v[202:205], v[74:77]
	v_mfma_f32_16x16x32_bf16 v[66:69], v[154:157], v[202:205], v[66:69]
	s_setprio 0
	s_setprio 1
	v_mfma_f32_16x16x32_bf16 v[126:129], v[158:161], v[174:177], v[126:129]
	v_mfma_f32_16x16x32_bf16 v[118:121], v[166:169], v[174:177], v[118:121]
	v_mfma_f32_16x16x32_bf16 v[110:113], v[158:161], v[182:185], v[110:113]
	v_mfma_f32_16x16x32_bf16 v[102:105], v[166:169], v[182:185], v[102:105]
	v_mfma_f32_16x16x32_bf16 v[94:97], v[158:161], v[190:193], v[94:97]
	v_mfma_f32_16x16x32_bf16 v[86:89], v[166:169], v[190:193], v[86:89]
	v_mfma_f32_16x16x32_bf16 v[78:81], v[158:161], v[198:201], v[78:81]
	v_mfma_f32_16x16x32_bf16 v[70:73], v[166:169], v[198:201], v[70:73]
	v_mfma_f32_16x16x32_bf16 v[126:129], v[162:165], v[178:181], v[126:129]
	v_mfma_f32_16x16x32_bf16 v[118:121], v[170:173], v[178:181], v[118:121]
	v_mfma_f32_16x16x32_bf16 v[110:113], v[162:165], v[186:189], v[110:113]
	v_mfma_f32_16x16x32_bf16 v[102:105], v[170:173], v[186:189], v[102:105]
	v_mfma_f32_16x16x32_bf16 v[94:97], v[162:165], v[194:197], v[94:97]
	v_mfma_f32_16x16x32_bf16 v[86:89], v[170:173], v[194:197], v[86:89]
	v_mfma_f32_16x16x32_bf16 v[78:81], v[162:165], v[202:205], v[78:81]
	v_mfma_f32_16x16x32_bf16 v[70:73], v[170:173], v[202:205], v[70:73]
	s_setprio 0
	s_barrier
	s_add_i32 s26, s48, s28
	v_lshl_add_u64 v[206:207], v[206:207], 0, s[44:45]
	s_mov_b32 m0, s26
	ds_read_b128 v[174:177], v141 offset:49152
	ds_read_b128 v[178:181], v141 offset:50176
	ds_read_b128 v[182:185], v141 offset:51200
	ds_read_b128 v[186:189], v141 offset:52224
	ds_read_b128 v[190:193], v141 offset:53248
	ds_read_b128 v[194:197], v141 offset:54272
	ds_read_b128 v[198:201], v141 offset:55296
	ds_read_b128 v[202:205], v141 offset:56320
	global_load_lds_dwordx4 v[206:207], off
	s_add_i32 m0, s26, 0x2000
	s_add_u32 s2, s2, 0x40080
	v_lshl_add_u64 v[206:207], v[218:219], 0, s[44:45]
	s_addc_u32 s3, s3, 0
	s_add_i32 s26, s49, s28
	global_load_lds_dwordx4 v[206:207], off
	v_lshl_add_u64 v[206:207], s[2:3], 0, v[132:133]
	s_mov_b32 m0, s26
	s_nop 0
	global_load_lds_dwordx4 v[206:207], off
	v_lshl_add_u64 v[206:207], s[2:3], 0, v[130:131]
	s_add_i32 m0, s26, 0x2000
	s_nop 0
	global_load_lds_dwordx4 v[206:207], off
	v_lshl_add_u64 v[206:207], v[222:223], 0, s[44:45]
	s_mov_b32 m0, s35
	s_nop 0
	global_load_lds_dwordx4 v[206:207], off
	v_lshl_add_u64 v[206:207], v[224:225], 0, s[44:45]
	s_mov_b32 m0, s36
	s_nop 0
	global_load_lds_dwordx4 v[206:207], off
	s_waitcnt vmcnt(8)
	s_waitcnt lgkmcnt(0)
	s_barrier
	s_setprio 1
	v_mfma_f32_16x16x32_bf16 v[58:61], v[142:145], v[174:177], v[58:61]
	v_mfma_f32_16x16x32_bf16 v[50:53], v[150:153], v[174:177], v[50:53]
	v_mfma_f32_16x16x32_bf16 v[42:45], v[142:145], v[182:185], v[42:45]
	v_mfma_f32_16x16x32_bf16 v[34:37], v[150:153], v[182:185], v[34:37]
	v_mfma_f32_16x16x32_bf16 v[26:29], v[142:145], v[190:193], v[26:29]
	v_mfma_f32_16x16x32_bf16 v[18:21], v[150:153], v[190:193], v[18:21]
	v_mfma_f32_16x16x32_bf16 v[10:13], v[142:145], v[198:201], v[10:13]
	v_mfma_f32_16x16x32_bf16 v[2:5], v[150:153], v[198:201], v[2:5]
	v_mfma_f32_16x16x32_bf16 v[58:61], v[146:149], v[178:181], v[58:61]
	v_mfma_f32_16x16x32_bf16 v[50:53], v[154:157], v[178:181], v[50:53]
	v_mfma_f32_16x16x32_bf16 v[42:45], v[146:149], v[186:189], v[42:45]
	v_mfma_f32_16x16x32_bf16 v[34:37], v[154:157], v[186:189], v[34:37]
	v_mfma_f32_16x16x32_bf16 v[26:29], v[146:149], v[194:197], v[26:29]
	v_mfma_f32_16x16x32_bf16 v[18:21], v[154:157], v[194:197], v[18:21]
	v_mfma_f32_16x16x32_bf16 v[10:13], v[146:149], v[202:205], v[10:13]
	v_mfma_f32_16x16x32_bf16 v[2:5], v[154:157], v[202:205], v[2:5]
	s_setprio 0
	s_setprio 1
	v_mfma_f32_16x16x32_bf16 v[62:65], v[158:161], v[174:177], v[62:65]
	v_mfma_f32_16x16x32_bf16 v[54:57], v[166:169], v[174:177], v[54:57]
	v_mfma_f32_16x16x32_bf16 v[46:49], v[158:161], v[182:185], v[46:49]
	v_mfma_f32_16x16x32_bf16 v[38:41], v[166:169], v[182:185], v[38:41]
	v_mfma_f32_16x16x32_bf16 v[30:33], v[158:161], v[190:193], v[30:33]
	v_mfma_f32_16x16x32_bf16 v[22:25], v[166:169], v[190:193], v[22:25]
	v_mfma_f32_16x16x32_bf16 v[14:17], v[158:161], v[198:201], v[14:17]
	v_mfma_f32_16x16x32_bf16 v[6:9], v[166:169], v[198:201], v[6:9]
	v_mfma_f32_16x16x32_bf16 v[62:65], v[162:165], v[178:181], v[62:65]
	v_mfma_f32_16x16x32_bf16 v[54:57], v[170:173], v[178:181], v[54:57]
	v_mfma_f32_16x16x32_bf16 v[46:49], v[162:165], v[186:189], v[46:49]
	v_mfma_f32_16x16x32_bf16 v[38:41], v[170:173], v[186:189], v[38:41]
	v_mfma_f32_16x16x32_bf16 v[30:33], v[162:165], v[194:197], v[30:33]
	v_mfma_f32_16x16x32_bf16 v[22:25], v[170:173], v[194:197], v[22:25]
	v_mfma_f32_16x16x32_bf16 v[14:17], v[162:165], v[202:205], v[14:17]
	v_mfma_f32_16x16x32_bf16 v[6:9], v[170:173], v[202:205], v[6:9]
	s_setprio 0
	s_barrier
	s_add_i32 s47, s47, 2
	s_add_u32 s4, s4, 0x100
	s_addc_u32 s5, s5, 0
	s_add_u32 s42, s42, 0x100
	s_addc_u32 s46, s46, 0
	s_cmp_gt_u32 s47, 13
	s_cbranch_scc0 .LBB0_783
	s_and_b64 vcc, exec, s[12:13]
	s_cbranch_vccz .LBB0_786
	s_barrier

.LBB0_849:
	s_add_u32 s2, s18, 0x100
	s_addc_u32 s3, s19, 0
	s_add_i32 s47, 0, 0x10000
	s_cmp_eq_u32 s46, 40
	s_cselect_b32 s23, s9, s3
	s_cselect_b32 s22, s8, s2
	v_add_u32_e32 v0, s47, v135
	s_cselect_b32 s21, s15, s42
	s_cselect_b32 s20, s14, s17
	s_add_i32 s48, 0, 0x14000
	ds_read_b128 v[146:149], v0
	ds_read_b128 v[150:153], v0 offset:1024
	ds_read_b128 v[154:157], v0 offset:2048
	ds_read_b128 v[158:161], v0 offset:3072
	v_add_u32_e32 v0, s48, v135
	ds_read_b128 v[162:165], v0
	ds_read_b128 v[166:169], v0 offset:1024
	ds_read_b128 v[170:173], v0 offset:2048
	ds_read_b128 v[174:177], v0 offset:3072
	v_lshl_add_u64 v[142:143], s[18:19], 0, v[138:139]
	s_add_i32 m0, s25, 0xc000
	ds_read_b128 v[178:181], v144
	ds_read_b128 v[182:185], v144 offset:1024
	ds_read_b128 v[186:189], v144 offset:2048
	ds_read_b128 v[190:193], v144 offset:3072
	ds_read_b128 v[194:197], v144 offset:4096
	ds_read_b128 v[198:201], v144 offset:5120
	ds_read_b128 v[202:205], v144 offset:6144
	ds_read_b128 v[222:225], v144 offset:7168
	global_load_lds_dwordx4 v[142:143], off
	v_lshl_add_u64 v[142:143], s[18:19], 0, v[140:141]
	s_add_i32 m0, s25, 0xe000
	s_nop 0
	global_load_lds_dwordx4 v[142:143], off
	s_waitcnt vmcnt(8)
	s_waitcnt lgkmcnt(0)
	s_barrier
	s_setprio 1
	v_mfma_f32_16x16x32_bf16 v[126:129], v[146:149], v[178:181], v[126:129]
	v_mfma_f32_16x16x32_bf16 v[122:125], v[154:157], v[178:181], v[122:125]
	v_mfma_f32_16x16x32_bf16 v[110:113], v[146:149], v[186:189], v[110:113]
	v_mfma_f32_16x16x32_bf16 v[106:109], v[154:157], v[186:189], v[106:109]
	v_mfma_f32_16x16x32_bf16 v[94:97], v[146:149], v[194:197], v[94:97]
	v_mfma_f32_16x16x32_bf16 v[90:93], v[154:157], v[194:197], v[90:93]
	v_mfma_f32_16x16x32_bf16 v[78:81], v[146:149], v[202:205], v[78:81]
	v_mfma_f32_16x16x32_bf16 v[74:77], v[154:157], v[202:205], v[74:77]
	v_mfma_f32_16x16x32_bf16 v[126:129], v[150:153], v[182:185], v[126:129]
	v_mfma_f32_16x16x32_bf16 v[122:125], v[158:161], v[182:185], v[122:125]
	v_mfma_f32_16x16x32_bf16 v[110:113], v[150:153], v[190:193], v[110:113]
	v_mfma_f32_16x16x32_bf16 v[106:109], v[158:161], v[190:193], v[106:109]
	v_mfma_f32_16x16x32_bf16 v[94:97], v[150:153], v[198:201], v[94:97]
	v_mfma_f32_16x16x32_bf16 v[90:93], v[158:161], v[198:201], v[90:93]
	v_mfma_f32_16x16x32_bf16 v[78:81], v[150:153], v[222:225], v[78:81]
	v_mfma_f32_16x16x32_bf16 v[74:77], v[158:161], v[222:225], v[74:77]
	s_setprio 0
	s_setprio 1
	v_mfma_f32_16x16x32_bf16 v[118:121], v[162:165], v[178:181], v[118:121]
	v_mfma_f32_16x16x32_bf16 v[114:117], v[170:173], v[178:181], v[114:117]
	v_mfma_f32_16x16x32_bf16 v[102:105], v[162:165], v[186:189], v[102:105]
	v_mfma_f32_16x16x32_bf16 v[98:101], v[170:173], v[186:189], v[98:101]
	v_mfma_f32_16x16x32_bf16 v[86:89], v[162:165], v[194:197], v[86:89]
	v_mfma_f32_16x16x32_bf16 v[82:85], v[170:173], v[194:197], v[82:85]
	v_mfma_f32_16x16x32_bf16 v[70:73], v[162:165], v[202:205], v[70:73]
	v_mfma_f32_16x16x32_bf16 v[66:69], v[170:173], v[202:205], v[66:69]
	v_mfma_f32_16x16x32_bf16 v[118:121], v[166:169], v[182:185], v[118:121]
	v_mfma_f32_16x16x32_bf16 v[114:117], v[174:177], v[182:185], v[114:117]
	v_mfma_f32_16x16x32_bf16 v[102:105], v[166:169], v[190:193], v[102:105]
	v_mfma_f32_16x16x32_bf16 v[98:101], v[174:177], v[190:193], v[98:101]
	v_mfma_f32_16x16x32_bf16 v[86:89], v[166:169], v[198:201], v[86:89]
	v_mfma_f32_16x16x32_bf16 v[82:85], v[174:177], v[198:201], v[82:85]
	v_mfma_f32_16x16x32_bf16 v[70:73], v[166:169], v[222:225], v[70:73]
	v_mfma_f32_16x16x32_bf16 v[66:69], v[174:177], v[222:225], v[66:69]
	s_setprio 0
	s_barrier
	s_add_i32 s18, s47, s24
	v_lshl_add_u64 v[142:143], s[20:21], 0, v[130:131]
	s_mov_b32 m0, s18
	ds_read_b128 v[178:181], v144 offset:16384
	ds_read_b128 v[182:185], v144 offset:17408
	ds_read_b128 v[186:189], v144 offset:18432
	ds_read_b128 v[190:193], v144 offset:19456
	ds_read_b128 v[194:197], v144 offset:20480
	ds_read_b128 v[198:201], v144 offset:21504
	ds_read_b128 v[202:205], v144 offset:22528
	ds_read_b128 v[222:225], v144 offset:23552
	global_load_lds_dwordx4 v[142:143], off
	s_add_i32 m0, s18, 0x2000
	s_add_u32 s18, s20, 0xb0000
	v_lshl_add_u64 v[206:207], s[20:21], 0, v[132:133]
	s_addc_u32 s19, s21, 0
	s_add_i32 s47, s48, s24
	global_load_lds_dwordx4 v[206:207], off
	v_lshl_add_u64 v[218:219], s[18:19], 0, v[130:131]
	s_mov_b32 m0, s47
	v_lshl_add_u64 v[226:227], s[22:23], 0, v[132:133]
	global_load_lds_dwordx4 v[218:219], off
	v_lshl_add_u64 v[218:219], s[18:19], 0, v[132:133]
	s_add_i32 m0, s47, 0x2000
	s_nop 0
	global_load_lds_dwordx4 v[218:219], off
	v_lshl_add_u64 v[218:219], s[22:23], 0, v[130:131]
	s_mov_b32 m0, s25
	s_nop 0
	global_load_lds_dwordx4 v[218:219], off
	s_mov_b32 m0, s26
	s_nop 0
	global_load_lds_dwordx4 v[226:227], off
	s_waitcnt vmcnt(8)
	s_waitcnt lgkmcnt(0)
	s_barrier
	s_setprio 1
	v_mfma_f32_16x16x32_bf16 v[62:65], v[146:149], v[178:181], v[62:65]
	v_mfma_f32_16x16x32_bf16 v[58:61], v[154:157], v[178:181], v[58:61]
	v_mfma_f32_16x16x32_bf16 v[46:49], v[146:149], v[186:189], v[46:49]
	v_mfma_f32_16x16x32_bf16 v[42:45], v[154:157], v[186:189], v[42:45]
	v_mfma_f32_16x16x32_bf16 v[30:33], v[146:149], v[194:197], v[30:33]
	v_mfma_f32_16x16x32_bf16 v[26:29], v[154:157], v[194:197], v[26:29]
	v_mfma_f32_16x16x32_bf16 v[14:17], v[146:149], v[202:205], v[14:17]
	v_mfma_f32_16x16x32_bf16 v[10:13], v[154:157], v[202:205], v[10:13]
	v_mfma_f32_16x16x32_bf16 v[62:65], v[150:153], v[182:185], v[62:65]
	v_mfma_f32_16x16x32_bf16 v[58:61], v[158:161], v[182:185], v[58:61]
	v_mfma_f32_16x16x32_bf16 v[46:49], v[150:153], v[190:193], v[46:49]
	v_mfma_f32_16x16x32_bf16 v[42:45], v[158:161], v[190:193], v[42:45]
	v_mfma_f32_16x16x32_bf16 v[30:33], v[150:153], v[198:201], v[30:33]
	v_mfma_f32_16x16x32_bf16 v[26:29], v[158:161], v[198:201], v[26:29]
	v_mfma_f32_16x16x32_bf16 v[14:17], v[150:153], v[222:225], v[14:17]
	v_mfma_f32_16x16x32_bf16 v[10:13], v[158:161], v[222:225], v[10:13]
	s_setprio 0
	s_setprio 1
	v_mfma_f32_16x16x32_bf16 v[54:57], v[162:165], v[178:181], v[54:57]
	v_mfma_f32_16x16x32_bf16 v[50:53], v[170:173], v[178:181], v[50:53]
	v_mfma_f32_16x16x32_bf16 v[38:41], v[162:165], v[186:189], v[38:41]
	v_mfma_f32_16x16x32_bf16 v[34:37], v[170:173], v[186:189], v[34:37]
	v_mfma_f32_16x16x32_bf16 v[22:25], v[162:165], v[194:197], v[22:25]
	v_mfma_f32_16x16x32_bf16 v[18:21], v[170:173], v[194:197], v[18:21]
	v_mfma_f32_16x16x32_bf16 v[6:9], v[162:165], v[202:205], v[6:9]
	v_mfma_f32_16x16x32_bf16 v[2:5], v[170:173], v[202:205], v[2:5]
	v_mfma_f32_16x16x32_bf16 v[54:57], v[166:169], v[182:185], v[54:57]
	v_mfma_f32_16x16x32_bf16 v[50:53], v[174:177], v[182:185], v[50:53]
	v_mfma_f32_16x16x32_bf16 v[38:41], v[166:169], v[190:193], v[38:41]
	v_mfma_f32_16x16x32_bf16 v[34:37], v[174:177], v[190:193], v[34:37]
	v_mfma_f32_16x16x32_bf16 v[22:25], v[166:169], v[198:201], v[22:25]
	v_mfma_f32_16x16x32_bf16 v[18:21], v[174:177], v[198:201], v[18:21]
	v_mfma_f32_16x16x32_bf16 v[6:9], v[166:169], v[222:225], v[6:9]
	v_mfma_f32_16x16x32_bf16 v[2:5], v[174:177], v[222:225], v[2:5]
	s_setprio 0
	s_barrier
	s_add_i32 s47, 0, 0x18000
	v_add_u32_e32 v0, s47, v135
	s_add_i32 s48, 0, 0x1c000
	ds_read_b128 v[146:149], v0
	ds_read_b128 v[150:153], v0 offset:1024
	ds_read_b128 v[154:157], v0 offset:2048
	ds_read_b128 v[158:161], v0 offset:3072
	v_add_u32_e32 v0, s48, v135
	ds_read_b128 v[162:165], v0
	ds_read_b128 v[166:169], v0 offset:1024
	ds_read_b128 v[170:173], v0 offset:2048
	ds_read_b128 v[174:177], v0 offset:3072
	s_add_u32 s18, s22, 0xb0000
	s_addc_u32 s19, s23, 0
	s_mov_b32 m0, s27
	v_lshl_add_u64 v[228:229], s[18:19], 0, v[130:131]
	ds_read_b128 v[178:181], v144 offset:32768
	ds_read_b128 v[182:185], v144 offset:33792
	ds_read_b128 v[186:189], v144 offset:34816
	ds_read_b128 v[190:193], v144 offset:35840
	ds_read_b128 v[194:197], v144 offset:36864
	ds_read_b128 v[198:201], v144 offset:37888
	ds_read_b128 v[202:205], v144 offset:38912
	ds_read_b128 v[222:225], v144 offset:39936
	global_load_lds_dwordx4 v[228:229], off
	v_lshl_add_u64 v[228:229], s[18:19], 0, v[132:133]
	s_mov_b32 m0, s28
	s_nop 0
	global_load_lds_dwordx4 v[228:229], off
	s_waitcnt vmcnt(8)
	s_waitcnt lgkmcnt(0)
	s_barrier
	s_setprio 1
	v_mfma_f32_16x16x32_bf16 v[126:129], v[146:149], v[178:181], v[126:129]
	v_mfma_f32_16x16x32_bf16 v[122:125], v[154:157], v[178:181], v[122:125]
	v_mfma_f32_16x16x32_bf16 v[110:113], v[146:149], v[186:189], v[110:113]
	v_mfma_f32_16x16x32_bf16 v[106:109], v[154:157], v[186:189], v[106:109]
	v_mfma_f32_16x16x32_bf16 v[94:97], v[146:149], v[194:197], v[94:97]
	v_mfma_f32_16x16x32_bf16 v[90:93], v[154:157], v[194:197], v[90:93]
	v_mfma_f32_16x16x32_bf16 v[78:81], v[146:149], v[202:205], v[78:81]
	v_mfma_f32_16x16x32_bf16 v[74:77], v[154:157], v[202:205], v[74:77]
	v_mfma_f32_16x16x32_bf16 v[126:129], v[150:153], v[182:185], v[126:129]
	v_mfma_f32_16x16x32_bf16 v[122:125], v[158:161], v[182:185], v[122:125]
	v_mfma_f32_16x16x32_bf16 v[110:113], v[150:153], v[190:193], v[110:113]
	v_mfma_f32_16x16x32_bf16 v[106:109], v[158:161], v[190:193], v[106:109]
	v_mfma_f32_16x16x32_bf16 v[94:97], v[150:153], v[198:201], v[94:97]
	v_mfma_f32_16x16x32_bf16 v[90:93], v[158:161], v[198:201], v[90:93]
	v_mfma_f32_16x16x32_bf16 v[78:81], v[150:153], v[222:225], v[78:81]
	v_mfma_f32_16x16x32_bf16 v[74:77], v[158:161], v[222:225], v[74:77]
	s_setprio 0
	s_setprio 1
	v_mfma_f32_16x16x32_bf16 v[118:121], v[162:165], v[178:181], v[118:121]
	v_mfma_f32_16x16x32_bf16 v[114:117], v[170:173], v[178:181], v[114:117]
	v_mfma_f32_16x16x32_bf16 v[102:105], v[162:165], v[186:189], v[102:105]
	v_mfma_f32_16x16x32_bf16 v[98:101], v[170:173], v[186:189], v[98:101]
	v_mfma_f32_16x16x32_bf16 v[86:89], v[162:165], v[194:197], v[86:89]
	v_mfma_f32_16x16x32_bf16 v[82:85], v[170:173], v[194:197], v[82:85]
	v_mfma_f32_16x16x32_bf16 v[70:73], v[162:165], v[202:205], v[70:73]
	v_mfma_f32_16x16x32_bf16 v[66:69], v[170:173], v[202:205], v[66:69]
	v_mfma_f32_16x16x32_bf16 v[118:121], v[166:169], v[182:185], v[118:121]
	v_mfma_f32_16x16x32_bf16 v[114:117], v[174:177], v[182:185], v[114:117]
	v_mfma_f32_16x16x32_bf16 v[102:105], v[166:169], v[190:193], v[102:105]
	v_mfma_f32_16x16x32_bf16 v[98:101], v[174:177], v[190:193], v[98:101]
	v_mfma_f32_16x16x32_bf16 v[86:89], v[166:169], v[198:201], v[86:89]
	v_mfma_f32_16x16x32_bf16 v[82:85], v[174:177], v[198:201], v[82:85]
	v_mfma_f32_16x16x32_bf16 v[70:73], v[166:169], v[222:225], v[70:73]
	v_mfma_f32_16x16x32_bf16 v[66:69], v[174:177], v[222:225], v[66:69]
	s_setprio 0
	s_barrier
	s_add_i32 s18, s47, s24
	v_lshl_add_u64 v[142:143], v[142:143], 0, s[44:45]
	s_mov_b32 m0, s18
	ds_read_b128 v[178:181], v144 offset:49152
	ds_read_b128 v[182:185], v144 offset:50176
	ds_read_b128 v[186:189], v144 offset:51200
	ds_read_b128 v[190:193], v144 offset:52224
	ds_read_b128 v[194:197], v144 offset:53248
	ds_read_b128 v[198:201], v144 offset:54272
	ds_read_b128 v[202:205], v144 offset:55296
	ds_read_b128 v[222:225], v144 offset:56320
	global_load_lds_dwordx4 v[142:143], off
	s_add_i32 m0, s18, 0x2000
	s_add_u32 s18, s20, 0xb0080
	v_lshl_add_u64 v[142:143], v[206:207], 0, s[44:45]
	s_addc_u32 s19, s21, 0
	s_add_i32 s20, s48, s24
	global_load_lds_dwordx4 v[142:143], off
	v_lshl_add_u64 v[142:143], s[18:19], 0, v[130:131]
	s_mov_b32 m0, s20
	s_nop 0
	global_load_lds_dwordx4 v[142:143], off
	v_lshl_add_u64 v[142:143], s[18:19], 0, v[132:133]
	s_add_i32 m0, s20, 0x2000
	s_nop 0
	global_load_lds_dwordx4 v[142:143], off
	v_lshl_add_u64 v[142:143], v[218:219], 0, s[44:45]
	s_mov_b32 m0, s31
	s_nop 0
	global_load_lds_dwordx4 v[142:143], off
	v_lshl_add_u64 v[142:143], v[226:227], 0, s[44:45]
	s_mov_b32 m0, s33
	s_nop 0
	global_load_lds_dwordx4 v[142:143], off
	s_waitcnt vmcnt(8)
	s_waitcnt lgkmcnt(0)
	s_barrier
	s_setprio 1
	v_mfma_f32_16x16x32_bf16 v[62:65], v[146:149], v[178:181], v[62:65]
	v_mfma_f32_16x16x32_bf16 v[58:61], v[154:157], v[178:181], v[58:61]
	v_mfma_f32_16x16x32_bf16 v[46:49], v[146:149], v[186:189], v[46:49]
	v_mfma_f32_16x16x32_bf16 v[42:45], v[154:157], v[186:189], v[42:45]
	v_mfma_f32_16x16x32_bf16 v[30:33], v[146:149], v[194:197], v[30:33]
	v_mfma_f32_16x16x32_bf16 v[26:29], v[154:157], v[194:197], v[26:29]
	v_mfma_f32_16x16x32_bf16 v[14:17], v[146:149], v[202:205], v[14:17]
	v_mfma_f32_16x16x32_bf16 v[10:13], v[154:157], v[202:205], v[10:13]
	v_mfma_f32_16x16x32_bf16 v[62:65], v[150:153], v[182:185], v[62:65]
	v_mfma_f32_16x16x32_bf16 v[58:61], v[158:161], v[182:185], v[58:61]
	v_mfma_f32_16x16x32_bf16 v[46:49], v[150:153], v[190:193], v[46:49]
	v_mfma_f32_16x16x32_bf16 v[42:45], v[158:161], v[190:193], v[42:45]
	v_mfma_f32_16x16x32_bf16 v[30:33], v[150:153], v[198:201], v[30:33]
	v_mfma_f32_16x16x32_bf16 v[26:29], v[158:161], v[198:201], v[26:29]
	v_mfma_f32_16x16x32_bf16 v[14:17], v[150:153], v[222:225], v[14:17]
	v_mfma_f32_16x16x32_bf16 v[10:13], v[158:161], v[222:225], v[10:13]
	s_setprio 0
	s_setprio 1
	v_mfma_f32_16x16x32_bf16 v[54:57], v[162:165], v[178:181], v[54:57]
	v_mfma_f32_16x16x32_bf16 v[50:53], v[170:173], v[178:181], v[50:53]
	v_mfma_f32_16x16x32_bf16 v[38:41], v[162:165], v[186:189], v[38:41]
	v_mfma_f32_16x16x32_bf16 v[34:37], v[170:173], v[186:189], v[34:37]
	v_mfma_f32_16x16x32_bf16 v[22:25], v[162:165], v[194:197], v[22:25]
	v_mfma_f32_16x16x32_bf16 v[18:21], v[170:173], v[194:197], v[18:21]
	v_mfma_f32_16x16x32_bf16 v[6:9], v[162:165], v[202:205], v[6:9]
	v_mfma_f32_16x16x32_bf16 v[2:5], v[170:173], v[202:205], v[2:5]
	v_mfma_f32_16x16x32_bf16 v[54:57], v[166:169], v[182:185], v[54:57]
	v_mfma_f32_16x16x32_bf16 v[50:53], v[174:177], v[182:185], v[50:53]
	v_mfma_f32_16x16x32_bf16 v[38:41], v[166:169], v[190:193], v[38:41]
	v_mfma_f32_16x16x32_bf16 v[34:37], v[174:177], v[190:193], v[34:37]
	v_mfma_f32_16x16x32_bf16 v[22:25], v[166:169], v[198:201], v[22:25]
	v_mfma_f32_16x16x32_bf16 v[18:21], v[174:177], v[198:201], v[18:21]
	v_mfma_f32_16x16x32_bf16 v[6:9], v[166:169], v[222:225], v[6:9]
	v_mfma_f32_16x16x32_bf16 v[2:5], v[174:177], v[222:225], v[2:5]
	s_setprio 0
	s_barrier
	s_add_i32 s46, s46, 2
	s_add_u32 s17, s17, 0x100
	s_addc_u32 s42, s42, 0
	s_cmp_gt_u32 s46, 41
	s_mov_b64 s[18:19], s[2:3]
	s_cbranch_scc0 .LBB0_849
	s_and_b64 vcc, exec, s[12:13]
	s_cbranch_vccz .LBB0_852
	s_barrier
